# MLA: each workgroup runs the short causal unit of its pair before the long one (better L2 reuse of the K/V stream start)
# baseline (speedup 1.0000x reference)
; __device__ __forceinline__ int hw_lane_id() { return (int)__builtin_amdgcn_mbcnt_hi(~0u, __builtin_amdgcn_mbcnt_lo(~0u, 0u)); }
; __device__ __forceinline__ void mla_unit2(LAS unsigned char* lds, const bf16_t* QB, const bf16_t* KB, const bf16_t* VT, bf16_t* OB, int b, int h, int qb, int wv) {
;     int tid_ = wv * 64 + hw_lane_id(); asm volatile("" : "+v"(tid_));
;     const int tid = tid_, lane = tid & 63, wid = __builtin_amdgcn_readfirstlane(tid >> 6), r = lane & 31, hh = lane >> 5;
;     const int q0 = qb * 512 + wid * 64;
;     const size_t rowbase = (size_t)b * SEQ;
;     bf16x8 qa[6], qbf[6];
;     { const bf16_t* qp = QB + (rowbase + q0 + r) * NQB + h * 96 + 8 * hh;
; #pragma unroll
;       for (int s = 0; s < 6; ++s) { qa[s] = *(const bf16x8*)(qp + 16 * s); qbf[s] = *(const bf16x8*)(qp + (size_t)32 * NQB + 16 * s); } }
;     f32x16 oa0, oa1, ob0, ob1;
; #pragma unroll
;     for (int i = 0; i < 16; ++i) { oa0[i] = 0.f; oa1[i] = 0.f; ob0[i] = 0.f; ob1[i] = 0.f; }
;     float ma = -INFINITY, mb = -INFINITY, la = 0.f, lb = 0.f;
;     const int ntiles = 8 * (qb + 1), nact = q0 / 64 + 1, tl = ntiles - 1;
;     const int kA_key = tid / 12, kA_part = tid % 12, kC_key = (512 + (tid & 255)) / 12, kC_part = (512 + (tid & 255)) % 12, v_d = tid >> 3, v_part = tid & 7;
;     const bf16_t* gKA = KB + (rowbase + kA_key) * NQB + h * 96 + kA_part * 8;
;     const bf16_t* gKC = KB + (rowbase + kC_key) * NQB + h * 96 + kC_part * 8;
;     const bf16_t* gV = VT + ((size_t)(b * 8 + h) * 64 + v_d) * SEQ + v_part * 8;
;     const int lKA = kA_key * MK_ROW + kA_part * 16, lKC = kC_key * MK_ROW + kC_part * 16, lV = MK_BYTES + v_d * MV_ROW + v_part * 16;
;     u32x4 ra = *(const u32x4*)gKA, rc = *(const u32x4*)gKC, rv = *(const u32x4*)gV;
;     __syncthreads();
;     *(LAS u32x4*)(lds + lKA) = ra; *(LAS u32x4*)(lds + lKC) = rc; *(LAS u32x4*)(lds + lV) = rv;
;     __syncthreads();
; __global__ void __launch_bounds__(512) fwd_megakernel(Params p) {
;     ...
;           for (int it = vcu; it < 512; it += G) {
;             const int itl = (it & 31) + 32 * (it >> 8), bh = (G == 256) ? ((it >> 5) & 7) * 8 + (itl >> 3) : (it >> 3), pr = (G == 256) ? (itl & 7) : (it & 7);
; #pragma unroll 1
;             for (int k = 0; k < 2; ++k) mla_unit2(lds, BIGP(ws, B_QB), BIGP(ws, B_KB), BIGP(ws, B_VT), BIGP(ws, B_OB), bh >> 3, bh & 7, k ? pr : 15 - pr, wave);
.LBB0_660:
	v_mov_b32_e32 v20, v194
	s_mov_b32 s12, 0x2aaaaaab
	s_xor_b64 s[30:31], s[0:1], -1
	v_mul_hi_i32 v0, v20, s12
	v_lshrrev_b32_e32 v2, 31, v0
	v_ashrrev_i32_e32 v0, 1, v0
	v_add_u32_e32 v14, v0, v2
	v_mul_lo_u32 v0, v14, 12
	v_sub_u32_e32 v24, v20, v0
	v_mov_b32_e32 v0, 0xff
	s_movk_i32 s12, 0x200
	v_bitop3_b16 v0, v20, s12, v0 bitop3:0xec
	s_mov_b32 s12, 0xaaab
	v_mul_u32_u24_sdwa v2, v0, s12 dst_sel:DWORD dst_unused:UNUSED_PAD src0_sel:WORD_0 src1_sel:DWORD
	v_lshrrev_b32_e32 v25, 19, v2
	v_mul_lo_u16_e32 v2, 12, v25
	v_ashrrev_i32_e32 v15, 31, v14
	v_sub_u16_e32 v0, v0, v2
	v_lshl_add_u64 v[2:3], s[4:5], 0, v[14:15]
	v_mov_b64_e32 v[4:5], s[8:9]
	s_and_b64 s[0:1], s[0:1], exec
	v_mad_u64_u32 v[6:7], s[16:17], v2, s33, v[4:5]
	v_lshlrev_b32_e32 v2, 3, v24
	s_cselect_b32 s12, s68, s69
	v_readfirstlane_b32 s0, v20
	v_mad_i32_i24 v7, v3, s33, v7
	v_ashrrev_i32_e32 v3, 31, v2
	s_lshl_b32 s75, s12, 9
	s_and_b32 s70, s0, 0xffffffc0
	v_lshl_add_u64 v[200:201], v[2:3], 1, v[6:7]
	v_or_b32_e32 v2, s4, v25
	s_add_i32 s70, s70, s75
	v_ashrrev_i32_e32 v16, 3, v20
	v_mad_u64_u32 v[2:3], s[16:17], v2, s33, v[4:5]
	v_mov_b32_e32 v22, 0x600
	s_ashr_i32 s0, s70, 31
	v_mad_i32_i24 v3, s5, v22, v3
	v_lshlrev_b32_e32 v0, 4, v0
	v_ashrrev_i32_e32 v17, 31, v16
	v_and_b32_e32 v15, 31, v20
	s_add_u32 s1, s4, s70
	v_lshl_add_u64 v[202:203], v[2:3], 0, v[0:1]
	v_lshlrev_b64 v[2:3], 14, v[16:17]
	v_lshlrev_b32_e32 v12, 4, v20
	v_bfe_u32 v17, v20, 5, 1
	v_or_b32_e32 v198, s1, v15
	v_mov_b64_e32 v[20:21], s[6:7]
	s_addc_u32 s16, s5, s0
	v_mad_u64_u32 v[20:21], s[0:1], v198, s33, v[20:21]
	v_mad_i32_i24 v21, s16, v22, v21
	v_lshlrev_b32_e32 v206, 4, v17
	v_mov_b32_e32 v207, v1
	v_lshl_add_u64 v[10:11], s[10:11], 0, v[2:3]
	v_and_b32_e32 v18, 0x70, v12
	v_mov_b32_e32 v19, v1
	v_lshl_add_u64 v[20:21], v[20:21], 0, v[206:207]
	s_mov_b32 s0, 0xc000
	v_lshl_add_u64 v[204:205], v[10:11], 0, v[18:19]
	v_add_co_u32_e32 v22, vcc, s0, v20
	global_load_dwordx4 v[2:5], v[200:201], off
	global_load_dwordx4 v[6:9], v[202:203], off
	global_load_dwordx4 v[10:13], v[204:205], off
	global_load_dwordx4 v[144:147], v[20:21], off
	v_addc_co_u32_e32 v23, vcc, 0, v21, vcc
	global_load_dwordx4 v[148:151], v[20:21], off offset:32
	global_load_dwordx4 v[152:155], v[20:21], off offset:64
	global_load_dwordx4 v[156:159], v[22:23], off offset:32
	global_load_dwordx4 v[160:163], v[22:23], off offset:64
	global_load_dwordx4 v[164:167], v[20:21], off offset:96
	global_load_dwordx4 v[168:171], v[20:21], off offset:128
	global_load_dwordx4 v[172:175], v[22:23], off offset:96
	global_load_dwordx4 v[176:179], v[22:23], off offset:128
	global_load_dwordx4 v[180:183], v[22:23], off
	global_load_dwordx4 v[184:187], v[20:21], off offset:160
	global_load_dwordx4 v[188:191], v[22:23], off offset:160
	s_movk_i32 s0, 0xd0
	v_mul_lo_u32 v14, v14, s0
	v_mul_lo_u16_e32 v19, 0xd0, v25
	s_lshl_b32 s0, s12, 3
	v_lshl_add_u32 v197, v24, 4, v14
	v_add_u32_e32 v207, v0, v19
	s_or_b32 s73, s0, 7
	v_add_u32_e32 v0, 0, v197
	v_add_u32_e32 v14, 0, v207
	v_mad_u64_u32 v[208:209], s[0:1], v16, s19, v[18:19]
	s_or_b32 s74, s70, 32
	s_waitcnt vmcnt(63) expcnt(7) lgkmcnt(15)
	s_barrier
	v_mul_u32_u24_e32 v209, 0xd0, v15
	v_or_b32_e32 v211, s70, v15
	v_mul_u32_u24_e32 v213, 0x90, v15
	v_or_b32_e32 v214, s74, v15
	v_mov_b32_e32 v15, v1
	v_lshlrev_b32_e32 v196, 3, v17
	v_lshlrev_b32_e32 v212, 2, v17
	s_mov_b32 s71, 0
	s_mov_b32 s100, 1
	s_ashr_i32 s72, s70, 6
	v_mov_b32_e32 v199, s16
	s_addk_i32 s75, 0x200
	v_mov_b32_e32 v223, 0
	s_waitcnt vmcnt(14)
	ds_write_b128 v0, v[2:5]
	s_waitcnt vmcnt(13)
	ds_write_b128 v14, v[6:9]
	v_add_u32_e32 v0, 0, v208
	v_mov_b32_e32 v14, v1
	s_waitcnt vmcnt(12)
	ds_write_b128 v0, v[10:13] offset:13312
	v_mov_b32_e32 v0, v1
	v_mov_b32_e32 v2, v1
	v_mov_b32_e32 v3, v1
	v_mov_b32_e32 v4, v1
	v_mov_b32_e32 v5, v1
	v_mov_b32_e32 v6, v1
	v_mov_b32_e32 v7, v1
	v_mov_b32_e32 v8, v1
	v_mov_b32_e32 v9, v1
	v_mov_b32_e32 v10, v1
	v_mov_b32_e32 v11, v1
	v_mov_b32_e32 v12, v1
	v_mov_b32_e32 v13, v1
	v_mov_b64_e32 v[30:31], v[14:15]
	v_mov_b64_e32 v[46:47], v[14:15]
	v_mov_b64_e32 v[62:63], v[14:15]
	v_mov_b64_e32 v[78:79], v[14:15]
	v_mov_b32_e32 v222, 0
	s_mov_b32 s0, 0
	v_mov_b32_e32 v225, 0
	v_mov_b32_e32 v224, 0
	v_mov_b64_e32 v[28:29], v[12:13]
	v_mov_b64_e32 v[26:27], v[10:11]
	v_mov_b64_e32 v[24:25], v[8:9]
	v_mov_b64_e32 v[22:23], v[6:7]
	v_mov_b64_e32 v[20:21], v[4:5]
	v_mov_b64_e32 v[18:19], v[2:3]
	v_mov_b64_e32 v[16:17], v[0:1]
	v_mov_b64_e32 v[44:45], v[12:13]
	v_mov_b64_e32 v[42:43], v[10:11]
	v_mov_b64_e32 v[40:41], v[8:9]
	v_mov_b64_e32 v[38:39], v[6:7]
	v_mov_b64_e32 v[36:37], v[4:5]
	v_mov_b64_e32 v[34:35], v[2:3]
	v_mov_b64_e32 v[32:33], v[0:1]
	v_mov_b64_e32 v[60:61], v[12:13]
	v_mov_b64_e32 v[58:59], v[10:11]
	v_mov_b64_e32 v[56:57], v[8:9]
	v_mov_b64_e32 v[54:55], v[6:7]
	v_mov_b64_e32 v[52:53], v[4:5]
	v_mov_b64_e32 v[50:51], v[2:3]
	v_mov_b64_e32 v[48:49], v[0:1]
	v_mov_b64_e32 v[76:77], v[12:13]
	v_mov_b64_e32 v[74:75], v[10:11]
	v_mov_b64_e32 v[72:73], v[8:9]
	v_mov_b64_e32 v[70:71], v[6:7]
	v_mov_b64_e32 v[68:69], v[4:5]
	v_mov_b64_e32 v[66:67], v[2:3]
	v_mov_b64_e32 v[64:65], v[0:1]
	s_waitcnt lgkmcnt(0)
	s_barrier
